# out-proj k-loop (both layers): global loads of k-tile kt+1 issued at the top of the iteration instead of behind the 4th k-step (own staging registers for the two loads that landed in fragment register
# speedup vs baseline: 1.0097x; 1.0018x over previous
.LBB0_620:
	s_add_i32 s24, s4, 1
	s_and_b32 s5, s24, 56
	s_cmp_eq_u32 s5, 8
	s_cselect_b32 s5, s13, 0x3000000
	s_add_u32 s5, s86, s5
	s_addc_u32 s25, s87, 0
	s_cmp_lt_u32 s4, 7
	s_cselect_b32 s4, s8, s25
	s_cselect_b32 s5, s7, s5
	s_and_b32 s25, s22, 0x1c0
	s_add_u32 s5, s5, s21
	s_addc_u32 s26, s4, 0
	s_lshl_b32 s4, s25, 1
	s_add_u32 s4, s5, s4
	s_addc_u32 s5, s26, 0
	v_lshl_add_u64 v[204:205], v[136:137], 0, s[0:1]
	v_add_co_u32_e32 v196, vcc, s14, v204
	s_nop 1
	v_addc_co_u32_e32 v197, vcc, 0, v205, vcc
	v_add_co_u32_e32 v168, vcc, s15, v204
	s_nop 1
	v_addc_co_u32_e32 v169, vcc, 0, v205, vcc
	v_add_co_u32_e32 v172, vcc, s16, v204
	s_nop 1
	v_addc_co_u32_e32 v173, vcc, 0, v205, vcc
	v_add_co_u32_e32 v176, vcc, s17, v204
	s_nop 1
	v_addc_co_u32_e32 v177, vcc, 0, v205, vcc
	global_load_dwordx4 v[196:199], v[196:197], off offset:128
	s_nop 0
	global_load_dwordx4 v[168:171], v[168:169], off offset:128
	s_nop 0
	global_load_dwordx4 v[172:175], v[172:173], off offset:128
	s_nop 0
	global_load_dwordx4 v[176:179], v[176:177], off offset:128
	s_nop 0
	s_and_b32 s98, s24, 56
	s_cmp_eq_u32 s98, 8
	s_cselect_b64 vcc, -1, 0
	s_sub_i32 s98, s24, 8
	s_lshl_b32 s98, s98, 21
	s_lshl_b32 s99, s19, 2
	s_add_u32 s98, s98, s99
	s_add_u32 s98, s98, 0xa000000
	s_add_u32 s98, s86, s98
	s_addc_u32 s99, s87, 0
	s_cbranch_vccnz .Lyb_ld_L0
	v_lshl_add_u64 v[206:207], s[4:5], 0, v[208:209]
	v_lshl_add_u64 v[184:185], v[206:207], 0, v[128:129]
	v_lshl_add_u64 v[188:189], v[206:207], 0, v[130:131]
	v_lshl_add_u64 v[192:193], v[206:207], 0, v[132:133]
	v_lshl_add_u64 v[200:201], v[206:207], 0, v[134:135]
	global_load_dwordx4 v[184:187], v[184:185], off
	s_nop 0
	global_load_dwordx4 v[188:191], v[188:189], off
	s_nop 0
	global_load_dwordx4 v[192:195], v[192:193], off
	s_nop 0
	global_load_dwordx4 v[200:203], v[200:201], off
	s_branch .Lyb_ld_done_L0
.Lyb_ld_L0:
	global_load_dwordx4 v[184:187], v230, s[98:99]
	global_load_dwordx4 v[188:191], v239, s[98:99]
	global_load_dwordx4 v[192:195], v240, s[98:99]
	global_load_dwordx4 v[200:203], v241, s[98:99]
.Lyb_ld_done_L0:
	s_and_b32 s25, s23, 0x10000
	s_add_i32 s25, s25, 16
	v_add_u32_e32 v141, s25, v139
	v_add3_u32 v142, v141, v166, v164
	v_add3_u32 v141, v141, v165, v164
	ds_read_b128 v[146:149], v142
	ds_read_b128 v[150:153], v141 offset:32768
	ds_read_b128 v[154:157], v142 offset:4096
	ds_read_b128 v[158:161], v141 offset:36864
	s_waitcnt lgkmcnt(2)
	v_mfma_f32_32x32x16_bf16 v[112:127], v[146:149], v[150:153], v[112:127]
	v_add_u32_e32 v141, s25, v138
	s_add_i32 s23, s23, 0x10000
	s_waitcnt lgkmcnt(0)
	v_mfma_f32_32x32x16_bf16 v[96:111], v[146:149], v[158:161], v[96:111]
	v_mfma_f32_32x32x16_bf16 v[80:95], v[154:157], v[150:153], v[80:95]
	v_mfma_f32_32x32x16_bf16 v[64:79], v[154:157], v[158:161], v[64:79]
	ds_read_b128 v[146:149], v142 offset:8192
	ds_read_b128 v[154:157], v142 offset:12288
	v_add3_u32 v142, v141, v166, v164
	v_add3_u32 v141, v141, v165, v164
	s_waitcnt lgkmcnt(1)
	v_mfma_f32_32x32x16_bf16 v[48:63], v[146:149], v[150:153], v[48:63]
	v_mfma_f32_32x32x16_bf16 v[32:47], v[146:149], v[158:161], v[32:47]
	s_waitcnt lgkmcnt(0)
	v_mfma_f32_32x32x16_bf16 v[16:31], v[154:157], v[150:153], v[16:31]
	v_mfma_f32_32x32x16_bf16 v[0:15], v[154:157], v[158:161], v[0:15]
	ds_read_b128 v[146:149], v142
	ds_read_b128 v[150:153], v141 offset:32768
	ds_read_b128 v[154:157], v142 offset:4096
	ds_read_b128 v[158:161], v141 offset:36864
	v_add_u32_e32 v141, s25, v144
	s_waitcnt lgkmcnt(2)
	v_mfma_f32_32x32x16_bf16 v[112:127], v[146:149], v[150:153], v[112:127]
	s_waitcnt lgkmcnt(0)
	v_mfma_f32_32x32x16_bf16 v[96:111], v[146:149], v[158:161], v[96:111]
	v_mfma_f32_32x32x16_bf16 v[80:95], v[154:157], v[150:153], v[80:95]
	v_mfma_f32_32x32x16_bf16 v[64:79], v[154:157], v[158:161], v[64:79]
	ds_read_b128 v[146:149], v142 offset:8192
	ds_read_b128 v[154:157], v142 offset:12288
	v_add3_u32 v142, v141, v166, v164
	v_add3_u32 v141, v141, v165, v164
	s_waitcnt lgkmcnt(1)
	v_mfma_f32_32x32x16_bf16 v[48:63], v[146:149], v[150:153], v[48:63]
	v_mfma_f32_32x32x16_bf16 v[32:47], v[146:149], v[158:161], v[32:47]
	s_waitcnt lgkmcnt(0)
	v_mfma_f32_32x32x16_bf16 v[16:31], v[154:157], v[150:153], v[16:31]
	v_mfma_f32_32x32x16_bf16 v[0:15], v[154:157], v[158:161], v[0:15]
	ds_read_b128 v[146:149], v142
	ds_read_b128 v[150:153], v141 offset:32768
	ds_read_b128 v[154:157], v142 offset:4096
	ds_read_b128 v[158:161], v141 offset:36864
	v_add_u32_e32 v141, s25, v167
	v_add3_u32 v145, v141, v166, v164
	v_add3_u32 v141, v141, v165, v164
	s_waitcnt lgkmcnt(2)
	v_mfma_f32_32x32x16_bf16 v[112:127], v[146:149], v[150:153], v[112:127]
	s_waitcnt lgkmcnt(0)
	v_mfma_f32_32x32x16_bf16 v[96:111], v[146:149], v[158:161], v[96:111]
	v_mfma_f32_32x32x16_bf16 v[80:95], v[154:157], v[150:153], v[80:95]
	v_mfma_f32_32x32x16_bf16 v[64:79], v[154:157], v[158:161], v[64:79]
	ds_read_b128 v[146:149], v142 offset:8192
	ds_read_b128 v[154:157], v142 offset:12288
	s_waitcnt lgkmcnt(1)
	v_mfma_f32_32x32x16_bf16 v[48:63], v[146:149], v[150:153], v[48:63]
	v_mfma_f32_32x32x16_bf16 v[32:47], v[146:149], v[158:161], v[32:47]
	s_waitcnt lgkmcnt(0)
	v_mfma_f32_32x32x16_bf16 v[16:31], v[154:157], v[150:153], v[16:31]
	v_mfma_f32_32x32x16_bf16 v[0:15], v[154:157], v[158:161], v[0:15]
	ds_read_b128 v[146:149], v145
	ds_read_b128 v[150:153], v141 offset:32768
	ds_read_b128 v[154:157], v145 offset:4096
	ds_read_b128 v[158:161], v141 offset:36864
	s_waitcnt lgkmcnt(2)
	v_mfma_f32_32x32x16_bf16 v[112:127], v[146:149], v[150:153], v[112:127]
	s_waitcnt lgkmcnt(0)
	v_mfma_f32_32x32x16_bf16 v[96:111], v[146:149], v[158:161], v[96:111]
	s_and_b32 s5, s23, 0x10000
	v_mfma_f32_32x32x16_bf16 v[80:95], v[154:157], v[150:153], v[80:95]
	s_add_u32 s0, s0, 0x80
	s_addc_u32 s1, s1, 0
	s_add_i32 s22, s22, 64
	s_mov_b32 s4, s24
	v_add_u32_e32 v141, s5, v140
	s_cmpk_lg_i32 s0, 0xb80
	v_mfma_f32_32x32x16_bf16 v[64:79], v[154:157], v[158:161], v[64:79]
	ds_read_b128 v[154:157], v145 offset:8192
	ds_read_b128 v[180:183], v145 offset:12288
	s_waitcnt lgkmcnt(1)
	v_mfma_f32_32x32x16_bf16 v[48:63], v[154:157], v[150:153], v[48:63]
	v_mfma_f32_32x32x16_bf16 v[32:47], v[154:157], v[158:161], v[32:47]
	s_waitcnt vmcnt(7)
	ds_write_b128 v141, v[196:199] offset:32768
	s_waitcnt vmcnt(6)
	ds_write_b128 v141, v[168:171] offset:40960
	s_waitcnt vmcnt(5)
	ds_write_b128 v141, v[172:175] offset:49152
	s_waitcnt vmcnt(4)
	ds_write_b128 v141, v[176:179] offset:57344
	s_cbranch_vccnz .Lyb_wr_L0
	s_waitcnt vmcnt(3)
	ds_write_b128 v141, v[184:187]
	s_waitcnt vmcnt(2)
	ds_write_b128 v141, v[188:191] offset:8192
	s_waitcnt vmcnt(1)
	ds_write_b128 v141, v[192:195] offset:16384
	s_waitcnt vmcnt(0)
	ds_write_b128 v141, v[200:203] offset:24576
	s_branch .Lyb_wr_done_L0
.Lyb_wr_L0:
	v_add_u32_e32 v242, s5, v231
	v_add_u32_e32 v243, s5, v232
	v_add_u32_e32 v244, s5, v233
	v_add_u32_e32 v245, s5, v234
	v_add_u32_e32 v246, s5, v235
	v_add_u32_e32 v247, s5, v236
	v_add_u32_e32 v248, s5, v237
	v_add_u32_e32 v249, s5, v238
	s_waitcnt vmcnt(3)
	ds_write_b32 v242, v184
	ds_write_b32 v242, v185 offset:128
	ds_write_b32 v243, v186 offset:256
	ds_write_b32 v243, v187 offset:384
	s_waitcnt vmcnt(2)
	ds_write_b32 v244, v188
	ds_write_b32 v244, v189 offset:128
	ds_write_b32 v245, v190 offset:256
	ds_write_b32 v245, v191 offset:384
	s_waitcnt vmcnt(1)
	ds_write_b32 v246, v192
	ds_write_b32 v246, v193 offset:128
	ds_write_b32 v247, v194 offset:256
	ds_write_b32 v247, v195 offset:384
	s_waitcnt vmcnt(0)
	ds_write_b32 v248, v200
	ds_write_b32 v248, v201 offset:128
	ds_write_b32 v249, v202 offset:256
	ds_write_b32 v249, v203 offset:384

.LBB0_992:
	s_add_i32 s24, s4, 1
	s_and_b32 s5, s24, 56
	s_cmp_eq_u32 s5, 8
	s_cselect_b32 s5, s13, 0x3000000
	s_add_u32 s5, s86, s5
	s_addc_u32 s25, s87, 0
	s_cmp_lt_u32 s4, 7
	s_cselect_b32 s4, s8, s25
	s_cselect_b32 s5, s7, s5
	s_and_b32 s25, s22, 0x1c0
	s_add_u32 s5, s5, s21
	s_addc_u32 s26, s4, 0
	s_lshl_b32 s4, s25, 1
	s_add_u32 s4, s5, s4
	s_addc_u32 s5, s26, 0
	v_lshl_add_u64 v[210:211], v[136:137], 0, s[0:1]
	v_add_co_u32_e32 v202, vcc, s14, v210
	s_nop 1
	v_addc_co_u32_e32 v203, vcc, 0, v211, vcc
	v_add_co_u32_e32 v172, vcc, s15, v210
	s_nop 1
	v_addc_co_u32_e32 v173, vcc, 0, v211, vcc
	v_add_co_u32_e32 v178, vcc, s16, v210
	s_nop 1
	v_addc_co_u32_e32 v179, vcc, 0, v211, vcc
	v_add_co_u32_e32 v182, vcc, s17, v210
	s_nop 1
	v_addc_co_u32_e32 v183, vcc, 0, v211, vcc
	global_load_dwordx4 v[202:205], v[202:203], off offset:128
	s_nop 0
	global_load_dwordx4 v[172:175], v[172:173], off offset:128
	s_nop 0
	global_load_dwordx4 v[178:181], v[178:179], off offset:128
	s_nop 0
	global_load_dwordx4 v[182:185], v[182:183], off offset:128
	s_nop 0
	s_and_b32 s98, s24, 56
	s_cmp_eq_u32 s98, 8
	s_cselect_b64 vcc, -1, 0
	s_sub_i32 s98, s24, 8
	s_lshl_b32 s98, s98, 21
	s_lshl_b32 s99, s19, 2
	s_add_u32 s98, s98, s99
	s_add_u32 s98, s98, 0xa000000
	s_add_u32 s98, s86, s98
	s_addc_u32 s99, s87, 0
	s_cbranch_vccnz .Lyb_ld_L1
	v_lshl_add_u64 v[212:213], s[4:5], 0, v[164:165]
	v_lshl_add_u64 v[190:191], v[212:213], 0, v[128:129]
	v_lshl_add_u64 v[194:195], v[212:213], 0, v[130:131]
	v_lshl_add_u64 v[198:199], v[212:213], 0, v[132:133]
	v_lshl_add_u64 v[206:207], v[212:213], 0, v[134:135]
	global_load_dwordx4 v[190:193], v[190:191], off
	s_nop 0
	global_load_dwordx4 v[194:197], v[194:195], off
	s_nop 0
	global_load_dwordx4 v[198:201], v[198:199], off
	s_nop 0
	global_load_dwordx4 v[206:209], v[206:207], off
	s_branch .Lyb_ld_done_L1
.Lyb_ld_L1:
	global_load_dwordx4 v[190:193], v230, s[98:99]
	global_load_dwordx4 v[194:197], v239, s[98:99]
	global_load_dwordx4 v[198:201], v240, s[98:99]
	global_load_dwordx4 v[206:209], v241, s[98:99]
.Lyb_ld_done_L1:
	s_and_b32 s25, s23, 0x10000
	s_add_i32 s25, s25, 16
	v_add_u32_e32 v145, s25, v143
	v_add3_u32 v162, v145, v140, v138
	v_add3_u32 v145, v145, v139, v138
	ds_read_b128 v[146:149], v162
	ds_read_b128 v[150:153], v145 offset:32768
	ds_read_b128 v[154:157], v162 offset:4096
	ds_read_b128 v[158:161], v145 offset:36864
	s_waitcnt lgkmcnt(2)
	v_mfma_f32_32x32x16_bf16 v[112:127], v[146:149], v[150:153], v[112:127]
	v_add_u32_e32 v145, s25, v142
	s_add_i32 s23, s23, 0x10000
	s_waitcnt lgkmcnt(0)
	v_mfma_f32_32x32x16_bf16 v[96:111], v[146:149], v[158:161], v[96:111]
	v_mfma_f32_32x32x16_bf16 v[80:95], v[154:157], v[150:153], v[80:95]
	v_mfma_f32_32x32x16_bf16 v[64:79], v[154:157], v[158:161], v[64:79]
	ds_read_b128 v[146:149], v162 offset:8192
	ds_read_b128 v[154:157], v162 offset:12288
	v_add3_u32 v162, v145, v140, v138
	v_add3_u32 v145, v145, v139, v138
	s_waitcnt lgkmcnt(1)
	v_mfma_f32_32x32x16_bf16 v[48:63], v[146:149], v[150:153], v[48:63]
	v_mfma_f32_32x32x16_bf16 v[32:47], v[146:149], v[158:161], v[32:47]
	s_waitcnt lgkmcnt(0)
	v_mfma_f32_32x32x16_bf16 v[16:31], v[154:157], v[150:153], v[16:31]
	v_mfma_f32_32x32x16_bf16 v[0:15], v[154:157], v[158:161], v[0:15]
	ds_read_b128 v[146:149], v162
	ds_read_b128 v[150:153], v145 offset:32768
	ds_read_b128 v[154:157], v162 offset:4096
	ds_read_b128 v[158:161], v145 offset:36864
	v_add_u32_e32 v145, s25, v141
	s_waitcnt lgkmcnt(2)
	v_mfma_f32_32x32x16_bf16 v[112:127], v[146:149], v[150:153], v[112:127]
	s_waitcnt lgkmcnt(0)
	v_mfma_f32_32x32x16_bf16 v[96:111], v[146:149], v[158:161], v[96:111]
	v_mfma_f32_32x32x16_bf16 v[80:95], v[154:157], v[150:153], v[80:95]
	v_mfma_f32_32x32x16_bf16 v[64:79], v[154:157], v[158:161], v[64:79]
	ds_read_b128 v[146:149], v162 offset:8192
	ds_read_b128 v[154:157], v162 offset:12288
	v_add3_u32 v162, v145, v140, v138
	v_add3_u32 v145, v145, v139, v138
	s_waitcnt lgkmcnt(1)
	v_mfma_f32_32x32x16_bf16 v[48:63], v[146:149], v[150:153], v[48:63]
	v_mfma_f32_32x32x16_bf16 v[32:47], v[146:149], v[158:161], v[32:47]
	s_waitcnt lgkmcnt(0)
	v_mfma_f32_32x32x16_bf16 v[16:31], v[154:157], v[150:153], v[16:31]
	v_mfma_f32_32x32x16_bf16 v[0:15], v[154:157], v[158:161], v[0:15]
	ds_read_b128 v[146:149], v162
	ds_read_b128 v[150:153], v145 offset:32768
	ds_read_b128 v[154:157], v162 offset:4096
	ds_read_b128 v[158:161], v145 offset:36864
	v_add_u32_e32 v145, s25, v170
	v_add3_u32 v171, v145, v140, v138
	v_add3_u32 v145, v145, v139, v138
	s_waitcnt lgkmcnt(2)
	v_mfma_f32_32x32x16_bf16 v[112:127], v[146:149], v[150:153], v[112:127]
	s_waitcnt lgkmcnt(0)
	v_mfma_f32_32x32x16_bf16 v[96:111], v[146:149], v[158:161], v[96:111]
	v_mfma_f32_32x32x16_bf16 v[80:95], v[154:157], v[150:153], v[80:95]
	v_mfma_f32_32x32x16_bf16 v[64:79], v[154:157], v[158:161], v[64:79]
	ds_read_b128 v[146:149], v162 offset:8192
	ds_read_b128 v[154:157], v162 offset:12288
	s_waitcnt lgkmcnt(1)
	v_mfma_f32_32x32x16_bf16 v[48:63], v[146:149], v[150:153], v[48:63]
	v_mfma_f32_32x32x16_bf16 v[32:47], v[146:149], v[158:161], v[32:47]
	s_waitcnt lgkmcnt(0)
	v_mfma_f32_32x32x16_bf16 v[16:31], v[154:157], v[150:153], v[16:31]
	v_mfma_f32_32x32x16_bf16 v[0:15], v[154:157], v[158:161], v[0:15]
	ds_read_b128 v[146:149], v171
	ds_read_b128 v[150:153], v145 offset:32768
	ds_read_b128 v[154:157], v171 offset:4096
	ds_read_b128 v[158:161], v145 offset:36864
	s_waitcnt lgkmcnt(2)
	v_mfma_f32_32x32x16_bf16 v[112:127], v[146:149], v[150:153], v[112:127]
	s_waitcnt lgkmcnt(0)
	v_mfma_f32_32x32x16_bf16 v[96:111], v[146:149], v[158:161], v[96:111]
	s_and_b32 s5, s23, 0x10000
	v_mfma_f32_32x32x16_bf16 v[80:95], v[154:157], v[150:153], v[80:95]
	s_add_u32 s0, s0, 0x80
	s_addc_u32 s1, s1, 0
	s_add_i32 s22, s22, 64
	s_mov_b32 s4, s24
	v_add_u32_e32 v145, s5, v144
	s_cmpk_lg_i32 s0, 0xb80
	v_mfma_f32_32x32x16_bf16 v[64:79], v[154:157], v[158:161], v[64:79]
	ds_read_b128 v[154:157], v171 offset:8192
	ds_read_b128 v[186:189], v171 offset:12288
	s_waitcnt lgkmcnt(1)
	v_mfma_f32_32x32x16_bf16 v[48:63], v[154:157], v[150:153], v[48:63]
	v_mfma_f32_32x32x16_bf16 v[32:47], v[154:157], v[158:161], v[32:47]
	s_waitcnt vmcnt(7)
	ds_write_b128 v145, v[202:205] offset:32768
	s_waitcnt vmcnt(6)
	ds_write_b128 v145, v[172:175] offset:40960
	s_waitcnt vmcnt(5)
	ds_write_b128 v145, v[178:181] offset:49152
	s_waitcnt vmcnt(4)
	ds_write_b128 v145, v[182:185] offset:57344
	s_cbranch_vccnz .Lyb_wr_L1
	s_waitcnt vmcnt(3)
	ds_write_b128 v145, v[190:193]
	s_waitcnt vmcnt(2)
	ds_write_b128 v145, v[194:197] offset:8192
	s_waitcnt vmcnt(1)
	ds_write_b128 v145, v[198:201] offset:16384
	s_waitcnt vmcnt(0)
	ds_write_b128 v145, v[206:209] offset:24576
	s_branch .Lyb_wr_done_L1
.Lyb_wr_L1:
	v_add_u32_e32 v242, s5, v231
	v_add_u32_e32 v243, s5, v232
	v_add_u32_e32 v244, s5, v233
	v_add_u32_e32 v245, s5, v234
	v_add_u32_e32 v246, s5, v235
	v_add_u32_e32 v247, s5, v236
	v_add_u32_e32 v248, s5, v237
	v_add_u32_e32 v249, s5, v238
	s_waitcnt vmcnt(3)
	ds_write_b32 v242, v190
	ds_write_b32 v242, v191 offset:128
	ds_write_b32 v243, v192 offset:256
	ds_write_b32 v243, v193 offset:384
	s_waitcnt vmcnt(2)
	ds_write_b32 v244, v194
	ds_write_b32 v244, v195 offset:128
	ds_write_b32 v245, v196 offset:256
	ds_write_b32 v245, v197 offset:384
	s_waitcnt vmcnt(1)
	ds_write_b32 v246, v198
	ds_write_b32 v246, v199 offset:128
	ds_write_b32 v247, v200 offset:256
	ds_write_b32 v247, v201 offset:384
	s_waitcnt vmcnt(0)
	ds_write_b32 v248, v206
	ds_write_b32 v248, v207 offset:128
	ds_write_b32 v249, v208 offset:256
	ds_write_b32 v249, v209 offset:384
